# strategy 2 on the P0 and P10 row-RMSNorm loops: 16 loop-invariant gain vectors hoisted into VGPRs before the loop, the per-store-pair load/vmcnt(0) ladder removed
# baseline (speedup 1.0000x reference)
; #define GAS __attribute__((address_space(1)))
; __device__ __forceinline__ unsigned pk2(float lo, float hi) { return pg8::cvt_pk_bf16(lo, hi); }
; __device__ __forceinline__ unsigned pk4_fp8(float a, float b, float c, float d) { unsigned w = 0u; w = __builtin_amdgcn_cvt_pk_fp8_f32(a, b, w, false); w = __builtin_amdgcn_cvt_pk_fp8_f32(c, d, w, true); return w; }
; #define KOUT() ((float*)karg_u64<128>())
; __device__ __forceinline__ void rms_row_to_bf16(const float* xrow, const float* g, bf16* orow, int lane, unsigned char* o8row = nullptr) {
;     const GAS f32x4* xr = (const GAS f32x4*)xrow + lane;
;     f32x4 v[16]; float s = 0.f;
; #pragma unroll
;     for (int j = 0; j < 16; ++j) { v[j] = xr[64 * j]; s += (v[j].x * v[j].x + v[j].y * v[j].y) + (v[j].z * v[j].z + v[j].w * v[j].w); }
;     const float inv = 1.0f / sqrtf(wave_sum(s) * (1.f / DM) + EPS);
;     const GAS f32x4* gr = (const GAS f32x4*)g + lane;
;     GAS v2u* o8 = (GAS v2u*)orow + lane;
; #pragma unroll
;     for (int j = 0; j < 16; ++j) { const f32x4 gg = gr[64 * j]; const float a = v[j].x * inv * gg.x, b = v[j].y * inv * gg.y, c = v[j].z * inv * gg.z, d = v[j].w * inv * gg.w;
;         v2u w; w.x = pk2(a, b); w.y = pk2(c, d); o8[64 * j] = w;
;         if (o8row) ((GAS unsigned*)o8row)[lane + 64 * j] = pk4_fp8(a, b, c, d); }
; __global__ void __launch_bounds__(NWAVES * 64, 2) fwd_kernel(Args args) {
;     ...
;         const float* xp = KIN(0); const float* xs = KIN(1); const float* g_mix = KIN(2); bf16* NB = (bf16*)(ws + WS_R1);
;         for (int m = gw; m < T_ALL; m += NGW) rms_row_to_bf16(m < T_P ? xp + (size_t)m * DM : xs + (size_t)(m - T_P) * DM, g_mix, NB + (size_t)m * DM, lane, (unsigned char*)KOUT() + N8_OFF + (size_t)m * DM);
.LBB0_70:
	s_or_b64 exec, exec, s[14:15]
	s_load_dwordx2 s[4:5], s[0:1], 0
	s_waitcnt lgkmcnt(0)
	s_load_dwordx2 s[6:7], s[0:1], 8
	s_waitcnt lgkmcnt(0)
	s_load_dwordx2 s[8:9], s[0:1], 16
	s_waitcnt lgkmcnt(0)
	s_cmpk_gt_i32 s10, 0x5fff
	v_mbcnt_lo_u32_b32 v1, -1, 0
	s_cbranch_scc1 .LBB0_75
	v_mov_b32_e32 v67, 0
	v_lshlrev_b32_e32 v66, 4, v38
	v_lshl_add_u64 v[68:69], s[8:9], 0, v[66:67]
	s_mov_b64 s[8:9], 0x1000
	v_lshl_add_u64 v[70:71], v[68:69], 0, s[8:9]
	s_mov_b64 s[8:9], 0x1400
	v_lshl_add_u64 v[72:73], v[68:69], 0, s[8:9]
	s_mov_b64 s[8:9], 0x1800
	v_lshl_add_u64 v[74:75], v[68:69], 0, s[8:9]
	s_mov_b64 s[8:9], 0x1c00
	v_lshl_add_u64 v[76:77], v[68:69], 0, s[8:9]
	s_mov_b64 s[8:9], 0x2000
	v_lshl_add_u64 v[78:79], v[68:69], 0, s[8:9]
	s_mov_b64 s[8:9], 0x2400
	v_lshl_add_u64 v[80:81], v[68:69], 0, s[8:9]
	s_mov_b64 s[8:9], 0x2800
	v_lshl_add_u64 v[82:83], v[68:69], 0, s[8:9]
	s_mov_b64 s[8:9], 0x2c00
	v_lshl_add_u64 v[84:85], v[68:69], 0, s[8:9]
	s_mov_b64 s[8:9], 0x3000
	v_lshl_add_u64 v[86:87], v[68:69], 0, s[8:9]
	s_mov_b64 s[8:9], 0x3400
	s_add_u32 s18, s12, 0x14a00000
	v_lshl_add_u64 v[88:89], v[68:69], 0, s[8:9]
	s_mov_b64 s[8:9], 0x3800
	s_addc_u32 s19, s13, 0
	v_lshl_add_u64 v[90:91], v[68:69], 0, s[8:9]
	s_mov_b64 s[8:9], 0x3c00
	s_ashr_i32 s11, s10, 31
	v_lshl_add_u64 v[92:93], v[68:69], 0, s[8:9]
	s_ashr_i32 s69, s68, 31
	s_lshl_b64 s[8:9], s[10:11], 14
	v_mbcnt_hi_u32_b32 v99, -1, v1
	s_add_u32 s8, s4, s8
	v_and_b32_e32 v2, 64, v99
	s_addc_u32 s9, s5, s9
	s_lshl_b64 s[12:13], s[68:69], 14
	s_mov_b32 s15, 0
	v_lshlrev_b32_e32 v66, 4, v38
	s_movk_i32 s24, 0x1000
	s_movk_i32 s25, 0x2000
	s_movk_i32 s26, 0x3000
	v_add_u32_e32 v100, 64, v2
	v_xor_b32_e32 v101, 1, v99
	v_xor_b32_e32 v102, 2, v99
	v_xor_b32_e32 v103, 4, v99
	v_xor_b32_e32 v104, 8, v99
	v_xor_b32_e32 v105, 16, v99
	v_xor_b32_e32 v106, 32, v99
	v_mov_b32_e32 v107, 0x358637bd
	s_mov_b32 s27, 0xf800000
	v_mov_b32_e32 v108, 0x260
	v_lshlrev_b32_e32 v94, 3, v38
	v_mov_b32_e32 v95, v67
	v_lshlrev_b32_e32 v96, 2, v38
	v_mov_b32_e32 v97, v67
	s_mov_b64 s[16:17], 0x5600000
	s_mov_b32 s28, 0x5600000
	global_load_dwordx4 v[150:153], v[68:69], off
	global_load_dwordx4 v[154:157], v[68:69], off offset:1024
	global_load_dwordx4 v[158:161], v[68:69], off offset:2048
	global_load_dwordx4 v[162:165], v[68:69], off offset:3072
	global_load_dwordx4 v[166:169], v[70:71], off
	global_load_dwordx4 v[170:173], v[72:73], off
	global_load_dwordx4 v[174:177], v[74:75], off
	global_load_dwordx4 v[178:181], v[76:77], off
	global_load_dwordx4 v[182:185], v[78:79], off
	global_load_dwordx4 v[186:189], v[80:81], off
	global_load_dwordx4 v[190:193], v[82:83], off
	global_load_dwordx4 v[194:197], v[84:85], off
	global_load_dwordx4 v[198:201], v[86:87], off
	global_load_dwordx4 v[202:205], v[88:89], off
	global_load_dwordx4 v[206:209], v[90:91], off
	global_load_dwordx4 v[210:213], v[92:93], off
	s_waitcnt vmcnt(0)
	s_branch .LBB0_73
.LBB0_72:
	s_load_dwordx2 s[20:21], s[0:1], 0x80
	s_waitcnt lgkmcnt(0)
	global_load_dwordx4 v[62:65], v66, s[22:23]
	global_load_dwordx4 v[58:61], v66, s[22:23] offset:1024
	global_load_dwordx4 v[42:45], v66, s[22:23] offset:3072
	v_lshl_add_u64 v[2:3], s[22:23], 0, v[66:67]
	global_load_dwordx4 v[54:57], v66, s[22:23] offset:2048
	v_add_co_u32_e32 v110, vcc, s25, v2
	s_lshl_b64 s[30:31], s[4:5], 12
	s_nop 0
	v_addc_co_u32_e32 v111, vcc, 0, v3, vcc
	global_load_dwordx4 v[50:53], v[110:111], off offset:-4096
	v_add_co_u32_e32 v4, vcc, s24, v2
	s_lshl_b64 s[22:23], s[4:5], 13
	s_nop 0
	v_addc_co_u32_e32 v5, vcc, 0, v3, vcc
	global_load_dwordx4 v[34:37], v[4:5], off offset:2048
	global_load_dwordx4 v[46:49], v[4:5], off offset:1024
	global_load_dwordx4 v[38:41], v[4:5], off offset:3072
	global_load_dwordx4 v[22:25], v[110:111], off offset:1024
	global_load_dwordx4 v[30:33], v[110:111], off
	global_load_dwordx4 v[26:29], v[110:111], off offset:2048
	v_add_co_u32_e32 v112, vcc, s26, v2
	s_add_u32 s22, s18, s22
	s_nop 0
	v_addc_co_u32_e32 v113, vcc, 0, v3, vcc
	global_load_dwordx4 v[18:21], v[110:111], off offset:3072
	global_load_dwordx4 v[10:13], v[112:113], off
	global_load_dwordx4 v[14:17], v[112:113], off offset:1024
	global_load_dwordx4 v[6:9], v[112:113], off offset:2048
	global_load_dwordx4 v[2:5], v[112:113], off offset:3072
	v_cmp_lt_i32_e32 vcc, v101, v100
	s_addc_u32 s23, s19, s23
	s_waitcnt vmcnt(0)
; #define GAS __attribute__((address_space(1)))
; __device__ __forceinline__ float wave_sum(float v) {
; #pragma unroll
;     for (int o = 1; o < 64; o <<= 1) v += __shfl_xor(v, o);
;     return v;
; __device__ __forceinline__ void rms_row_to_bf16(const float* xrow, const float* g, bf16* orow, int lane, unsigned char* o8row = nullptr) {
;     ...
;     for (int j = 0; j < 16; ++j) { v[j] = xr[64 * j]; s += (v[j].x * v[j].x + v[j].y * v[j].y) + (v[j].z * v[j].z + v[j].w * v[j].w); }
;     const float inv = 1.0f / sqrtf(wave_sum(s) * (1.f / DM) + EPS);
;     const GAS f32x4* gr = (const GAS f32x4*)g + lane;
;     GAS v2u* o8 = (GAS v2u*)orow + lane;
; #pragma unroll
;     for (int j = 0; j < 16; ++j) { const f32x4 gg = gr[64 * j]; const float a = v[j].x * inv * gg.x, b = v[j].y * inv * gg.y, c = v[j].z * inv * gg.z, d = v[j].w * inv * gg.w;
	v_pk_mul_f32 v[110:111], v[64:65], v[64:65]
	v_pk_mul_f32 v[112:113], v[62:63], v[62:63]
	v_pk_mul_f32 v[114:115], v[60:61], v[60:61]
	v_pk_mul_f32 v[116:117], v[58:59], v[58:59]
	v_pk_mov_b32 v[120:121], v[112:113], v[110:111] op_sel:[1,0]
	v_mov_b32_e32 v113, v111
	v_pk_mov_b32 v[110:111], v[116:117], v[114:115] op_sel:[1,0]
	v_mov_b32_e32 v117, v115
	v_mul_f32_e32 v98, v55, v55
	v_mul_f32_e32 v118, v57, v57
	v_pk_add_f32 v[112:113], v[120:121], v[112:113]
	v_pk_add_f32 v[110:111], v[110:111], v[116:117]
	v_mul_f32_e32 v109, v42, v42
	v_mul_f32_e32 v133, v43, v43
	v_mul_f32_e32 v127, v44, v44
	v_mul_f32_e32 v134, v45, v45
	v_pk_fma_f32 v[114:115], v[54:55], v[54:55], v[98:99] op_sel_hi:[1,1,0]
	v_pk_fma_f32 v[118:119], v[56:57], v[56:57], v[118:119] op_sel_hi:[1,1,0]
	v_pk_add_f32 v[112:113], v[112:113], v[112:113] op_sel:[0,1] op_sel_hi:[1,0]
	v_pk_add_f32 v[110:111], v[110:111], v[110:111] op_sel:[0,1] op_sel_hi:[1,0]
	v_pk_mul_f32 v[122:123], v[52:53], v[52:53]
	v_pk_mul_f32 v[124:125], v[50:51], v[50:51]
	v_mov_b32_e32 v115, v127
	v_mov_b32_e32 v119, v134
	v_mov_b32_e32 v113, v109
	v_mov_b32_e32 v111, v133
	v_pk_mov_b32 v[116:117], v[124:125], v[122:123] op_sel:[1,0]
	v_mov_b32_e32 v125, v123
	v_pk_add_f32 v[114:115], v[114:115], v[118:119]
	v_pk_add_f32 v[110:111], v[112:113], v[110:111]
	v_mul_f32_e32 v98, v47, v47
	v_mul_f32_e32 v126, v49, v49
	v_pk_add_f32 v[116:117], v[116:117], v[124:125]
	v_pk_add_f32 v[110:111], v[110:111], v[114:115]
	v_mul_f32_e32 v135, v34, v34
	v_mul_f32_e32 v136, v35, v35
	v_mul_f32_e32 v137, v36, v36
	v_mul_f32_e32 v138, v37, v37
	v_pk_fma_f32 v[120:121], v[46:47], v[46:47], v[98:99] op_sel_hi:[1,1,0]
	v_pk_fma_f32 v[122:123], v[48:49], v[48:49], v[126:127] op_sel_hi:[1,1,0]
	v_pk_add_f32 v[116:117], v[116:117], v[116:117] op_sel:[0,1] op_sel_hi:[1,0]
	v_pk_add_f32 v[110:111], v[110:111], v[110:111] op_sel:[0,1] op_sel_hi:[1,0]
	v_pk_mul_f32 v[128:129], v[40:41], v[40:41]
	v_pk_mul_f32 v[130:131], v[38:39], v[38:39]
	v_mov_b32_e32 v121, v137
	v_mov_b32_e32 v123, v138
	v_mov_b32_e32 v117, v136
	v_mov_b32_e32 v111, v135
	v_pk_mov_b32 v[126:127], v[130:131], v[128:129] op_sel:[1,0]
	v_mov_b32_e32 v131, v129
	v_pk_add_f32 v[120:121], v[120:121], v[122:123]
	v_pk_add_f32 v[110:111], v[110:111], v[116:117]
	v_mul_f32_e32 v132, v31, v31
	v_pk_add_f32 v[118:119], v[126:127], v[130:131]
	v_pk_add_f32 v[110:111], v[110:111], v[120:121]
	v_mul_f32_e32 v98, v33, v33
	v_mul_f32_e32 v139, v22, v22
	v_mul_f32_e32 v140, v23, v23
	v_mul_f32_e32 v141, v24, v24
	v_mul_f32_e32 v142, v25, v25
	v_pk_fma_f32 v[128:129], v[30:31], v[30:31], v[132:133] op_sel_hi:[1,1,0]
	v_pk_add_f32 v[118:119], v[118:119], v[118:119] op_sel:[0,1] op_sel_hi:[1,0]
	v_pk_add_f32 v[110:111], v[110:111], v[110:111] op_sel:[0,1] op_sel_hi:[1,0]
	v_pk_fma_f32 v[112:113], v[32:33], v[32:33], v[98:99] op_sel_hi:[1,1,0]
	v_mov_b32_e32 v119, v140
	v_mov_b32_e32 v111, v139
	v_mov_b32_e32 v129, v141
	v_mov_b32_e32 v113, v142
	v_pk_add_f32 v[110:111], v[110:111], v[118:119]
	v_pk_add_f32 v[112:113], v[128:129], v[112:113]
	v_pk_mul_f32 v[114:115], v[26:27], v[26:27]
	v_pk_add_f32 v[110:111], v[110:111], v[112:113]
	v_pk_mul_f32 v[112:113], v[28:29], v[28:29]
	v_mul_f32_e32 v98, v10, v10
	v_pk_mov_b32 v[116:117], v[114:115], v[112:113] op_sel:[1,0]
	v_mov_b32_e32 v115, v113
	v_pk_add_f32 v[112:113], v[116:117], v[114:115]
	v_mul_f32_e32 v109, v11, v11
	v_pk_add_f32 v[110:111], v[110:111], v[110:111] op_sel:[0,1] op_sel_hi:[1,0]
	v_pk_add_f32 v[112:113], v[112:113], v[112:113] op_sel:[0,1] op_sel_hi:[1,0]
	v_mov_b32_e32 v111, v98
	v_mov_b32_e32 v113, v109
	v_mul_f32_e32 v98, v19, v19
	v_mul_f32_e32 v114, v12, v12
	v_pk_add_f32 v[110:111], v[110:111], v[112:113]
	v_pk_fma_f32 v[112:113], v[18:19], v[18:19], v[98:99] op_sel_hi:[1,1,0]
	v_mul_f32_e32 v98, v21, v21
	v_mul_f32_e32 v116, v13, v13
	v_mov_b32_e32 v113, v114
	v_pk_fma_f32 v[114:115], v[20:21], v[20:21], v[98:99] op_sel_hi:[1,1,0]
	v_mul_f32_e32 v98, v2, v2
	v_mov_b32_e32 v115, v116
	v_pk_add_f32 v[112:113], v[112:113], v[114:115]
	v_pk_mul_f32 v[114:115], v[14:15], v[14:15]
	v_pk_add_f32 v[110:111], v[110:111], v[112:113]
	v_pk_mul_f32 v[112:113], v[16:17], v[16:17]
	v_mul_f32_e32 v109, v3, v3
	v_pk_mov_b32 v[116:117], v[114:115], v[112:113] op_sel:[1,0]
	v_mov_b32_e32 v115, v113
	v_pk_add_f32 v[112:113], v[116:117], v[114:115]
	v_pk_add_f32 v[110:111], v[110:111], v[110:111] op_sel:[0,1] op_sel_hi:[1,0]
	v_pk_add_f32 v[112:113], v[112:113], v[112:113] op_sel:[0,1] op_sel_hi:[1,0]
	v_mov_b32_e32 v111, v98
	v_mov_b32_e32 v113, v109
	v_mul_f32_e32 v98, v7, v7
	v_mul_f32_e32 v114, v4, v4
	v_pk_add_f32 v[110:111], v[110:111], v[112:113]
	v_pk_fma_f32 v[112:113], v[6:7], v[6:7], v[98:99] op_sel_hi:[1,1,0]
	v_mul_f32_e32 v98, v9, v9
	v_mul_f32_e32 v116, v5, v5
	v_mov_b32_e32 v113, v114
	v_pk_fma_f32 v[114:115], v[8:9], v[8:9], v[98:99] op_sel_hi:[1,1,0]
	v_cndmask_b32_e32 v109, v99, v101, vcc
	v_mov_b32_e32 v115, v116
	v_pk_add_f32 v[112:113], v[112:113], v[114:115]
	v_lshlrev_b32_e32 v109, 2, v109
	v_pk_add_f32 v[110:111], v[110:111], v[112:113]
	v_cmp_lt_i32_e32 vcc, v102, v100
	v_add_f32_e32 v98, v110, v111
	s_nop 1
	v_mov_b64_e32 v[110:111], v[150:151]
	v_mov_b64_e32 v[112:113], v[152:153]
	ds_bpermute_b32 v109, v109, v98
	s_waitcnt lgkmcnt(0)
	v_add_f32_e32 v98, v98, v109
	v_cndmask_b32_e32 v109, v99, v102, vcc
	v_lshlrev_b32_e32 v109, 2, v109
	ds_bpermute_b32 v109, v109, v98
	v_cmp_lt_i32_e32 vcc, v103, v100
	s_waitcnt lgkmcnt(0)
	v_add_f32_e32 v98, v98, v109
	v_cndmask_b32_e32 v109, v99, v103, vcc
	v_lshlrev_b32_e32 v109, 2, v109
	ds_bpermute_b32 v109, v109, v98
	v_cmp_lt_i32_e32 vcc, v104, v100
	s_waitcnt lgkmcnt(0)
; #define GAS __attribute__((address_space(1)))
; __device__ __forceinline__ unsigned pk2(float lo, float hi) { return pg8::cvt_pk_bf16(lo, hi); }
; __device__ __forceinline__ unsigned pk4_fp8(float a, float b, float c, float d) { unsigned w = 0u; w = __builtin_amdgcn_cvt_pk_fp8_f32(a, b, w, false); w = __builtin_amdgcn_cvt_pk_fp8_f32(c, d, w, true); return w; }
; __device__ __forceinline__ void rms_row_to_bf16(const float* xrow, const float* g, bf16* orow, int lane, unsigned char* o8row = nullptr) {
;     ...
;     const float inv = 1.0f / sqrtf(wave_sum(s) * (1.f / DM) + EPS);
;     const GAS f32x4* gr = (const GAS f32x4*)g + lane;
;     GAS v2u* o8 = (GAS v2u*)orow + lane;
; #pragma unroll
;     for (int j = 0; j < 16; ++j) { const f32x4 gg = gr[64 * j]; const float a = v[j].x * inv * gg.x, b = v[j].y * inv * gg.y, c = v[j].z * inv * gg.z, d = v[j].w * inv * gg.w;
;         v2u w; w.x = pk2(a, b); w.y = pk2(c, d); o8[64 * j] = w;
;         if (o8row) ((GAS unsigned*)o8row)[lane + 64 * j] = pk4_fp8(a, b, c, d); }
	v_add_f32_e32 v98, v98, v109
	v_cndmask_b32_e32 v109, v99, v104, vcc
	v_lshlrev_b32_e32 v109, 2, v109
	ds_bpermute_b32 v109, v109, v98
	v_cmp_lt_i32_e32 vcc, v105, v100
	s_waitcnt lgkmcnt(0)
	v_add_f32_e32 v98, v98, v109
	v_cndmask_b32_e32 v109, v99, v105, vcc
	v_lshlrev_b32_e32 v109, 2, v109
	ds_bpermute_b32 v109, v109, v98
	v_cmp_lt_i32_e32 vcc, v106, v100
	s_waitcnt lgkmcnt(0)
	v_add_f32_e32 v98, v98, v109
	v_cndmask_b32_e32 v109, v99, v106, vcc
	v_lshlrev_b32_e32 v109, 2, v109
	ds_bpermute_b32 v109, v109, v98
	s_waitcnt lgkmcnt(0)
	v_add_f32_e32 v98, v98, v109
	v_fmamk_f32 v98, v98, 0x39800000, v107
	v_mul_f32_e32 v109, 0x4f800000, v98
	v_cmp_gt_f32_e32 vcc, s27, v98
	s_nop 1
	v_cndmask_b32_e32 v98, v98, v109, vcc
	v_sqrt_f32_e32 v109, v98
	s_nop 0
	v_add_u32_e32 v114, -1, v109
	v_fma_f32 v115, -v114, v109, v98
	v_cmp_ge_f32_e64 s[4:5], 0, v115
	v_add_u32_e32 v115, 1, v109
	s_nop 0
	v_cndmask_b32_e64 v114, v109, v114, s[4:5]
	v_fma_f32 v109, -v115, v109, v98
	v_cmp_lt_f32_e64 s[4:5], 0, v109
	s_nop 1
	v_cndmask_b32_e64 v109, v114, v115, s[4:5]
	v_mul_f32_e32 v114, 0x37800000, v109
	v_cndmask_b32_e32 v109, v109, v114, vcc
	v_cmp_class_f32_e32 vcc, v98, v108
	s_nop 1
	v_cndmask_b32_e32 v98, v109, v98, vcc
	v_div_scale_f32 v109, s[4:5], v98, v98, 1.0
	v_rcp_f32_e32 v114, v109
	s_add_u32 s4, s20, s30
	s_addc_u32 s5, s21, s31
	s_add_u32 s10, s10, s68
	v_fma_f32 v115, -v109, v114, 1.0
	v_fmac_f32_e32 v114, v115, v114
	v_div_scale_f32 v115, vcc, 1.0, v98, 1.0
	v_mul_f32_e32 v116, v115, v114
	v_fma_f32 v117, -v109, v116, v115
	v_fmac_f32_e32 v116, v117, v114
	v_fma_f32 v109, -v109, v116, v115
	v_div_fmas_f32 v109, v109, v114, v116
	v_div_fixup_f32 v98, v109, v98, 1.0
	v_pk_mul_f32 v[62:63], v[62:63], v[98:99] op_sel_hi:[1,0]
	v_mov_b32_e32 v109, 0
	v_pk_mul_f32 v[62:63], v[110:111], v[62:63]
	v_pk_mul_f32 v[64:65], v[64:65], v[98:99] op_sel_hi:[1,0]
	v_cvt_pk_fp8_f32 v109, v62, v63
	v_pk_mul_f32 v[64:65], v[112:113], v[64:65]
	v_cvt_pk_bf16_f32 v110, v62, v63
	v_cvt_pk_bf16_f32 v111, v64, v65
	v_cvt_pk_fp8_f32 v109, v64, v65 op_sel:[0,0,1]
	global_store_dwordx2 v94, v[110:111], s[22:23]
	v_lshl_add_u64 v[110:111], s[4:5], 0, v[96:97]
	v_add_co_u32_e32 v62, vcc, s28, v110
	v_pk_mul_f32 v[58:59], v[58:59], v[98:99] op_sel_hi:[1,0]
	s_nop 0
	v_addc_co_u32_e32 v63, vcc, 0, v111, vcc
	global_store_dword v[62:63], v109, off
	s_nop 1
	v_mov_b64_e32 v[62:63], v[154:155]
	v_mov_b64_e32 v[64:65], v[156:157]
	v_mov_b32_e32 v109, 0
	v_pk_mul_f32 v[60:61], v[60:61], v[98:99] op_sel_hi:[1,0]
	v_pk_mul_f32 v[54:55], v[54:55], v[98:99] op_sel_hi:[1,0]
	v_pk_mul_f32 v[56:57], v[56:57], v[98:99] op_sel_hi:[1,0]
	v_pk_mul_f32 v[42:43], v[42:43], v[98:99] op_sel_hi:[1,0]
	v_pk_mul_f32 v[44:45], v[44:45], v[98:99] op_sel_hi:[1,0]
	v_pk_mul_f32 v[50:51], v[50:51], v[98:99] op_sel_hi:[1,0]
	v_pk_mul_f32 v[46:47], v[46:47], v[98:99] op_sel_hi:[1,0]
	v_pk_mul_f32 v[34:35], v[34:35], v[98:99] op_sel_hi:[1,0]
	v_pk_mul_f32 v[36:37], v[36:37], v[98:99] op_sel_hi:[1,0]
	v_pk_mul_f32 v[38:39], v[38:39], v[98:99] op_sel_hi:[1,0]
	v_pk_mul_f32 v[30:31], v[30:31], v[98:99] op_sel_hi:[1,0]
	v_pk_mul_f32 v[32:33], v[32:33], v[98:99] op_sel_hi:[1,0]
	v_pk_mul_f32 v[22:23], v[22:23], v[98:99] op_sel_hi:[1,0]
	v_pk_mul_f32 v[24:25], v[24:25], v[98:99] op_sel_hi:[1,0]
	v_pk_mul_f32 v[26:27], v[26:27], v[98:99] op_sel_hi:[1,0]
	v_pk_mul_f32 v[18:19], v[18:19], v[98:99] op_sel_hi:[1,0]
	v_pk_mul_f32 v[20:21], v[20:21], v[98:99] op_sel_hi:[1,0]
	v_pk_mul_f32 v[10:11], v[10:11], v[98:99] op_sel_hi:[1,0]
	v_pk_mul_f32 v[12:13], v[12:13], v[98:99] op_sel_hi:[1,0]
	v_pk_mul_f32 v[14:15], v[14:15], v[98:99] op_sel_hi:[1,0]
	v_pk_mul_f32 v[6:7], v[6:7], v[98:99] op_sel_hi:[1,0]
	v_pk_mul_f32 v[8:9], v[8:9], v[98:99] op_sel_hi:[1,0]
	v_pk_mul_f32 v[2:3], v[2:3], v[98:99] op_sel_hi:[1,0]
	v_pk_mul_f32 v[4:5], v[4:5], v[98:99] op_sel_hi:[1,0]
	s_addc_u32 s11, s11, s69
	s_add_u32 s8, s8, s12
	s_addc_u32 s9, s9, s13
	s_cmpk_gt_i32 s10, 0x5fff
	v_pk_mul_f32 v[62:63], v[62:63], v[58:59]
	s_nop 0
	v_cvt_pk_fp8_f32 v109, v62, v63
	v_pk_mul_f32 v[60:61], v[64:65], v[60:61]
	v_cvt_pk_bf16_f32 v62, v62, v63
	v_cvt_pk_bf16_f32 v63, v60, v61
	v_cvt_pk_fp8_f32 v109, v60, v61 op_sel:[0,0,1]
	v_lshl_add_u64 v[58:59], v[110:111], 0, s[16:17]
	global_store_dwordx2 v94, v[62:63], s[22:23] offset:512
	global_store_dword v[58:59], v109, off offset:256
	s_nop 1
	v_mov_b64_e32 v[60:61], v[158:159]
	v_mov_b64_e32 v[62:63], v[160:161]
	v_mov_b32_e32 v64, 0
	v_pk_mul_f32 v[54:55], v[54:55], v[60:61]
	s_nop 0
	v_cvt_pk_fp8_f32 v64, v54, v55
	v_pk_mul_f32 v[56:57], v[56:57], v[62:63]
	v_cvt_pk_bf16_f32 v54, v54, v55
	v_cvt_pk_bf16_f32 v55, v56, v57
	v_cvt_pk_fp8_f32 v64, v56, v57 op_sel:[0,0,1]
	global_store_dwordx2 v94, v[54:55], s[22:23] offset:1024
	global_store_dword v[58:59], v64, off offset:512
	s_nop 1
	v_mov_b64_e32 v[54:55], v[162:163]
	v_mov_b64_e32 v[56:57], v[164:165]
	v_mov_b32_e32 v60, 0
	v_pk_mul_f32 v[42:43], v[42:43], v[54:55]
	s_nop 0
	v_cvt_pk_fp8_f32 v60, v42, v43
	v_pk_mul_f32 v[44:45], v[44:45], v[56:57]
	v_cvt_pk_bf16_f32 v42, v42, v43
	v_cvt_pk_bf16_f32 v43, v44, v45
	v_cvt_pk_fp8_f32 v60, v44, v45 op_sel:[0,0,1]
	global_store_dwordx2 v94, v[42:43], s[22:23] offset:1536
	global_store_dword v[58:59], v60, off offset:768
	s_nop 1
	v_mov_b64_e32 v[42:43], v[166:167]
	v_mov_b64_e32 v[44:45], v[168:169]
	v_mov_b32_e32 v54, 0
	v_pk_mul_f32 v[42:43], v[50:51], v[42:43]
	s_nop 0
	v_cvt_pk_fp8_f32 v54, v42, v43
	v_pk_mul_f32 v[50:51], v[52:53], v[98:99] op_sel_hi:[1,0]
	v_cvt_pk_bf16_f32 v42, v42, v43
; #define GAS __attribute__((address_space(1)))
; __device__ __forceinline__ unsigned pk2(float lo, float hi) { return pg8::cvt_pk_bf16(lo, hi); }
; __device__ __forceinline__ unsigned pk4_fp8(float a, float b, float c, float d) { unsigned w = 0u; w = __builtin_amdgcn_cvt_pk_fp8_f32(a, b, w, false); w = __builtin_amdgcn_cvt_pk_fp8_f32(c, d, w, true); return w; }
; __device__ __forceinline__ void rms_row_to_bf16(const float* xrow, const float* g, bf16* orow, int lane, unsigned char* o8row = nullptr) {
;     ...
; #pragma unroll
;     for (int j = 0; j < 16; ++j) { const f32x4 gg = gr[64 * j]; const float a = v[j].x * inv * gg.x, b = v[j].y * inv * gg.y, c = v[j].z * inv * gg.z, d = v[j].w * inv * gg.w;
;         v2u w; w.x = pk2(a, b); w.y = pk2(c, d); o8[64 * j] = w;
;         if (o8row) ((GAS unsigned*)o8row)[lane + 64 * j] = pk4_fp8(a, b, c, d); }
	v_pk_mul_f32 v[44:45], v[50:51], v[44:45]
	v_mov_b32_e32 v50, 0
	v_cvt_pk_fp8_f32 v54, v44, v45 op_sel:[0,0,1]
	v_cvt_pk_bf16_f32 v43, v44, v45
	global_store_dwordx2 v94, v[42:43], s[22:23] offset:2048
	global_store_dword v[58:59], v54, off offset:1024
	s_nop 1
	v_mov_b64_e32 v[42:43], v[170:171]
	v_mov_b64_e32 v[44:45], v[172:173]
	v_pk_mul_f32 v[42:43], v[46:47], v[42:43]
	s_nop 0
	v_cvt_pk_fp8_f32 v50, v42, v43
	v_pk_mul_f32 v[46:47], v[48:49], v[98:99] op_sel_hi:[1,0]
	v_cvt_pk_bf16_f32 v42, v42, v43
	v_pk_mul_f32 v[44:45], v[46:47], v[44:45]
	v_mov_b32_e32 v46, 0
	v_cvt_pk_fp8_f32 v50, v44, v45 op_sel:[0,0,1]
	v_cvt_pk_bf16_f32 v43, v44, v45
	global_store_dwordx2 v94, v[42:43], s[22:23] offset:2560
	global_store_dword v[58:59], v50, off offset:1280
	s_nop 1
	v_mov_b64_e32 v[42:43], v[174:175]
	v_mov_b64_e32 v[44:45], v[176:177]
	v_pk_mul_f32 v[34:35], v[34:35], v[42:43]
	s_nop 0
	v_cvt_pk_fp8_f32 v46, v34, v35
	v_pk_mul_f32 v[36:37], v[36:37], v[44:45]
	v_cvt_pk_bf16_f32 v34, v34, v35
	v_cvt_pk_bf16_f32 v35, v36, v37
	v_cvt_pk_fp8_f32 v46, v36, v37 op_sel:[0,0,1]
	global_store_dwordx2 v94, v[34:35], s[22:23] offset:3072
	global_store_dword v[58:59], v46, off offset:1536
	s_nop 1
	v_mov_b64_e32 v[34:35], v[178:179]
	v_mov_b64_e32 v[36:37], v[180:181]
	v_mov_b32_e32 v42, 0
	v_pk_mul_f32 v[34:35], v[38:39], v[34:35]
	s_nop 0
	v_cvt_pk_fp8_f32 v42, v34, v35
	v_pk_mul_f32 v[38:39], v[40:41], v[98:99] op_sel_hi:[1,0]
	v_cvt_pk_bf16_f32 v34, v34, v35
	v_pk_mul_f32 v[36:37], v[38:39], v[36:37]
	v_mov_b32_e32 v40, 0
	v_cvt_pk_fp8_f32 v42, v36, v37 op_sel:[0,0,1]
	v_cvt_pk_bf16_f32 v35, v36, v37
	global_store_dwordx2 v94, v[34:35], s[22:23] offset:3584
	global_store_dword v[58:59], v42, off offset:1792
	s_nop 1
	v_mov_b64_e32 v[34:35], v[182:183]
	v_mov_b64_e32 v[36:37], v[184:185]
	v_lshl_add_u64 v[38:39], s[22:23], 0, v[94:95]
	v_pk_mul_f32 v[30:31], v[30:31], v[34:35]
	s_nop 0
	v_cvt_pk_fp8_f32 v40, v30, v31
	v_pk_mul_f32 v[32:33], v[32:33], v[36:37]
	v_add_co_u32_e32 v34, vcc, s24, v38
	v_cvt_pk_fp8_f32 v40, v32, v33 op_sel:[0,0,1]
	s_nop 0
	v_addc_co_u32_e32 v35, vcc, 0, v39, vcc
	v_cvt_pk_bf16_f32 v30, v30, v31
	v_cvt_pk_bf16_f32 v31, v32, v33
	global_store_dwordx2 v[34:35], v[30:31], off
	global_store_dword v[58:59], v40, off offset:2048
	s_nop 1
	v_mov_b64_e32 v[30:31], v[186:187]
	v_mov_b64_e32 v[32:33], v[188:189]
	v_mov_b32_e32 v36, 0
	v_pk_mul_f32 v[22:23], v[22:23], v[30:31]
	s_nop 0
	v_cvt_pk_fp8_f32 v36, v22, v23
	v_pk_mul_f32 v[24:25], v[24:25], v[32:33]
	v_cvt_pk_bf16_f32 v22, v22, v23
	v_cvt_pk_bf16_f32 v23, v24, v25
	v_cvt_pk_fp8_f32 v36, v24, v25 op_sel:[0,0,1]
	global_store_dwordx2 v[34:35], v[22:23], off offset:512
	global_store_dword v[58:59], v36, off offset:2304
	s_nop 1
	v_mov_b64_e32 v[22:23], v[190:191]
	v_mov_b64_e32 v[24:25], v[192:193]
	v_mov_b32_e32 v30, 0
	v_pk_mul_f32 v[22:23], v[26:27], v[22:23]
	s_nop 0
	v_cvt_pk_fp8_f32 v30, v22, v23
	v_pk_mul_f32 v[26:27], v[28:29], v[98:99] op_sel_hi:[1,0]
	v_cvt_pk_bf16_f32 v22, v22, v23
	v_pk_mul_f32 v[24:25], v[26:27], v[24:25]
	v_mov_b32_e32 v26, 0
	v_cvt_pk_fp8_f32 v30, v24, v25 op_sel:[0,0,1]
	v_cvt_pk_bf16_f32 v23, v24, v25
	global_store_dwordx2 v[34:35], v[22:23], off offset:1024
	global_store_dword v[58:59], v30, off offset:2560
	s_nop 1
	v_mov_b64_e32 v[22:23], v[194:195]
	v_mov_b64_e32 v[24:25], v[196:197]
	v_pk_mul_f32 v[18:19], v[18:19], v[22:23]
	s_nop 0
	v_cvt_pk_fp8_f32 v26, v18, v19
	v_pk_mul_f32 v[20:21], v[20:21], v[24:25]
	v_cvt_pk_bf16_f32 v18, v18, v19
	v_cvt_pk_bf16_f32 v19, v20, v21
	v_cvt_pk_fp8_f32 v26, v20, v21 op_sel:[0,0,1]
	global_store_dwordx2 v[34:35], v[18:19], off offset:1536
	global_store_dword v[58:59], v26, off offset:2816
	s_nop 1
	v_mov_b64_e32 v[18:19], v[198:199]
	v_mov_b64_e32 v[20:21], v[200:201]
	v_mov_b32_e32 v22, 0
	v_pk_mul_f32 v[10:11], v[10:11], v[18:19]
	s_nop 0
	v_cvt_pk_fp8_f32 v22, v10, v11
	v_pk_mul_f32 v[12:13], v[12:13], v[20:21]
	v_cvt_pk_bf16_f32 v10, v10, v11
	v_cvt_pk_bf16_f32 v11, v12, v13
	v_cvt_pk_fp8_f32 v22, v12, v13 op_sel:[0,0,1]
	global_store_dwordx2 v[34:35], v[10:11], off offset:2048
	global_store_dword v[58:59], v22, off offset:3072
	s_nop 1
	v_mov_b64_e32 v[10:11], v[202:203]
	v_mov_b64_e32 v[12:13], v[204:205]
	v_mov_b32_e32 v18, 0
	v_pk_mul_f32 v[10:11], v[14:15], v[10:11]
	s_nop 0
	v_cvt_pk_fp8_f32 v18, v10, v11
	v_pk_mul_f32 v[14:15], v[16:17], v[98:99] op_sel_hi:[1,0]
	v_cvt_pk_bf16_f32 v10, v10, v11
	v_pk_mul_f32 v[12:13], v[14:15], v[12:13]
	v_mov_b32_e32 v14, 0
	v_cvt_pk_fp8_f32 v18, v12, v13 op_sel:[0,0,1]
	v_cvt_pk_bf16_f32 v11, v12, v13
	global_store_dwordx2 v[34:35], v[10:11], off offset:2560
	global_store_dword v[58:59], v18, off offset:3328
	s_nop 1
	v_mov_b64_e32 v[10:11], v[206:207]
	v_mov_b64_e32 v[12:13], v[208:209]
	v_pk_mul_f32 v[6:7], v[6:7], v[10:11]
	s_nop 0
	v_cvt_pk_fp8_f32 v14, v6, v7
	v_pk_mul_f32 v[8:9], v[8:9], v[12:13]
	v_cvt_pk_bf16_f32 v6, v6, v7
	v_cvt_pk_bf16_f32 v7, v8, v9
	v_cvt_pk_fp8_f32 v14, v8, v9 op_sel:[0,0,1]
	global_store_dwordx2 v[34:35], v[6:7], off offset:3072
	global_store_dword v[58:59], v14, off offset:3584
	s_nop 1
	v_mov_b64_e32 v[6:7], v[210:211]
	v_mov_b64_e32 v[8:9], v[212:213]
	v_mov_b32_e32 v10, 0
	v_pk_mul_f32 v[2:3], v[2:3], v[6:7]
	s_nop 0
	v_cvt_pk_fp8_f32 v10, v2, v3
	v_pk_mul_f32 v[4:5], v[4:5], v[8:9]
	v_cvt_pk_bf16_f32 v2, v2, v3
	v_cvt_pk_bf16_f32 v3, v4, v5
	v_cvt_pk_fp8_f32 v10, v4, v5 op_sel:[0,0,1]
	global_store_dwordx2 v[34:35], v[2:3], off offset:3584
	global_store_dword v[58:59], v10, off offset:3840
	s_cbranch_scc1 .LBB0_75

; #define GAS __attribute__((address_space(1)))
; #define KOUT() ((float*)karg_u64<128>())
; #define TVIEW() int tid = threadIdx.x; asm volatile("" : "+v"(tid)); const int lane = tid & 63, wave = __builtin_amdgcn_readfirstlane(tid >> 6); \
;     const int vcu = (G % 8 == 0) ? (bx % 8) * (G / 8) + bx / 8 : bx, gw = vcu * NWAVES + wave, NGW = G * NWAVES; (void)lane; (void)gw; (void)NGW; \
;     unsigned char* ws = KWS(); (void)ws
; __device__ __forceinline__ void rms_row_bf16_to_f32(const bf16* hrow, const float* g, float* orow, int lane) {
;     const GAS v4u* hr = (const GAS v4u*)hrow + lane;
;     v4u v[8]; float s = 0.f;
; #pragma unroll
;     for (int j = 0; j < 8; ++j) { v[j] = hr[64 * j];
; __global__ void __launch_bounds__(NWAVES * 64, 2) fwd_kernel(Args args) {
;     ...
;         TVIEW();
;         float* out = KOUT(); const float* g_fin = KIN(15);
;         const bf16* H2 = (const bf16*)(ws + WS_R1);
;         for (int m = gw; m < T_ALL; m += NGW) rms_row_bf16_to_f32(H2 + (size_t)m * DM, g_fin, out + (size_t)m * DM, lane);
.LBB0_1129:
	s_ashr_i32 s3, s4, 6
	s_load_dwordx2 s[4:5], s[0:1], 0x88
	s_waitcnt lgkmcnt(0)
	s_load_dwordx2 s[8:9], s[0:1], 0x80
	s_waitcnt lgkmcnt(0)
	s_lshl_b32 s2, s2, 3
	s_load_dwordx2 s[0:1], s[0:1], 0x78
	s_waitcnt lgkmcnt(0)
	s_add_i32 s2, s2, s3
	s_cmpk_gt_i32 s2, 0x5fff
	s_cbranch_scc1 .LBB0_1132
	v_mbcnt_hi_u32_b32 v1, -1, v1
	v_and_b32_e32 v2, 64, v1
	v_add_u32_e32 v2, 64, v2
	v_xor_b32_e32 v3, 1, v1
	v_cmp_lt_i32_e32 vcc, v3, v2
	v_and_b32_e32 v0, 63, v0
	v_mov_b32_e32 v25, 0
	v_cndmask_b32_e32 v3, v1, v3, vcc
	v_lshlrev_b32_e32 v67, 2, v3
	v_xor_b32_e32 v3, 2, v1
	v_cmp_lt_i32_e32 vcc, v3, v2
	v_lshlrev_b32_e32 v24, 5, v0
	s_ashr_i32 s3, s2, 31
	v_cndmask_b32_e32 v3, v1, v3, vcc
	v_lshlrev_b32_e32 v68, 2, v3
	v_xor_b32_e32 v3, 4, v1
	v_cmp_lt_i32_e32 vcc, v3, v2
	v_lshl_add_u64 v[26:27], s[0:1], 0, v[24:25]
	s_movk_i32 s10, 0x1000
	v_cndmask_b32_e32 v3, v1, v3, vcc
	v_lshlrev_b32_e32 v69, 2, v3
	v_xor_b32_e32 v3, 8, v1
	v_cmp_lt_i32_e32 vcc, v3, v2
	v_mov_b32_e32 v73, 0x358637bd
	v_mov_b32_e32 v74, 0x260
	v_cndmask_b32_e32 v3, v1, v3, vcc
	v_lshlrev_b32_e32 v70, 2, v3
	v_xor_b32_e32 v3, 16, v1
	v_cmp_lt_i32_e32 vcc, v3, v2
	s_movk_i32 s11, 0xd000
	s_movk_i32 s12, 0xe000
	v_cndmask_b32_e32 v3, v1, v3, vcc
	v_lshlrev_b32_e32 v71, 2, v3
	v_xor_b32_e32 v3, 32, v1
	v_cmp_lt_i32_e32 vcc, v3, v2
	v_or_b32_e32 v2, 0x1000, v24
	s_movk_i32 s13, 0xf000
	v_cndmask_b32_e32 v1, v1, v3, vcc
	v_mov_b32_e32 v3, v25
	v_lshl_add_u64 v[28:29], s[0:1], 0, v[2:3]
	v_or_b32_e32 v2, 0x1800, v24
	v_lshl_add_u64 v[30:31], s[0:1], 0, v[2:3]
	v_or_b32_e32 v2, 0x2000, v24
	v_lshl_add_u64 v[32:33], s[0:1], 0, v[2:3]
	v_or_b32_e32 v2, 0x2800, v24
	v_lshl_add_u64 v[34:35], s[0:1], 0, v[2:3]
	v_or_b32_e32 v2, 0x3000, v24
	v_lshl_add_u64 v[36:37], s[0:1], 0, v[2:3]
	v_or_b32_e32 v2, 0x3800, v24
	v_lshl_add_u64 v[38:39], s[0:1], 0, v[2:3]
	s_lshl_b64 s[0:1], s[2:3], 13
	s_add_u32 s0, s4, s0
	s_addc_u32 s1, s5, s1
	s_add_u32 s4, s0, 0x14a00000
	s_addc_u32 s5, s1, 0
	s_ashr_i32 s69, s68, 31
	s_lshl_b64 s[6:7], s[68:69], 13
	s_lshl_b64 s[0:1], s[2:3], 14
	s_add_u32 s0, s8, s0
	s_addc_u32 s1, s9, s1
	v_lshl_add_u64 v[2:3], s[0:1], 0, v[24:25]
	s_mov_b64 s[0:1], 0x3810
	v_lshlrev_b32_e32 v72, 2, v1
	v_lshl_add_u64 v[40:41], v[2:3], 0, s[0:1]
	s_lshl_b64 s[8:9], s[68:69], 14
	v_lshlrev_b32_e32 v24, 4, v0
	s_mov_b32 s3, 0xf800000
	global_load_dwordx4 v[150:153], v[26:27], off offset:16
	global_load_dwordx4 v[154:157], v[26:27], off
	global_load_dwordx4 v[158:161], v[26:27], off offset:2048
	global_load_dwordx4 v[162:165], v[26:27], off offset:2064
	global_load_dwordx4 v[166:169], v[28:29], off
	global_load_dwordx4 v[170:173], v[28:29], off offset:16
	global_load_dwordx4 v[174:177], v[30:31], off
	global_load_dwordx4 v[178:181], v[30:31], off offset:16
	global_load_dwordx4 v[182:185], v[32:33], off
	global_load_dwordx4 v[186:189], v[32:33], off offset:16
	global_load_dwordx4 v[190:193], v[34:35], off
	global_load_dwordx4 v[194:197], v[34:35], off offset:16
	global_load_dwordx4 v[198:201], v[36:37], off
	global_load_dwordx4 v[202:205], v[36:37], off offset:16
	global_load_dwordx4 v[206:209], v[38:39], off
	global_load_dwordx4 v[210:213], v[38:39], off offset:16
	s_waitcnt vmcnt(0)
.LBB0_1131:
	v_add_co_u32_e32 v62, vcc, s11, v40
	global_load_dwordx4 v[8:11], v24, s[4:5] offset:1024
	global_load_dwordx4 v[16:19], v24, s[4:5] offset:2048
	global_load_dwordx4 v[12:15], v24, s[4:5]
	global_load_dwordx4 v[20:23], v24, s[4:5] offset:3072
	v_lshl_add_u64 v[42:43], s[4:5], 0, v[24:25]
	v_addc_co_u32_e32 v63, vcc, -1, v41, vcc
	v_add_co_u32_e32 v46, vcc, s10, v42
	s_nop 1
	v_mov_b64_e32 v[0:1], v[150:151]
	v_mov_b64_e32 v[2:3], v[152:153]
	s_nop 1
	v_mov_b64_e32 v[4:5], v[154:155]
	v_mov_b64_e32 v[6:7], v[156:157]
	v_addc_co_u32_e32 v47, vcc, 0, v43, vcc
	global_load_dwordx4 v[42:45], v[46:47], off
	global_load_dwordx4 v[76:79], v[46:47], off offset:1024
	global_load_dwordx4 v[80:83], v[46:47], off offset:2048
	global_load_dwordx4 v[84:87], v[46:47], off offset:3072
	s_add_i32 s2, s2, s68
	s_add_u32 s4, s4, s6
	s_addc_u32 s5, s5, s7
	s_cmpk_gt_i32 s2, 0x5fff
	s_waitcnt vmcnt(0)
	v_and_b32_e32 v91, 0xffff0000, v9
	v_and_b32_e32 v90, 0xffff0000, v8
	v_and_b32_e32 v105, 0xffff0000, v14
	v_and_b32_e32 v107, 0xffff0000, v15
	v_and_b32_e32 v109, 0xffff0000, v12
	v_and_b32_e32 v111, 0xffff0000, v13
	v_and_b32_e32 v95, 0xffff0000, v11
	v_and_b32_e32 v94, 0xffff0000, v10
	v_lshlrev_b32_e32 v104, 16, v14
	v_lshlrev_b32_e32 v106, 16, v15
	v_lshlrev_b32_e32 v108, 16, v12
	v_lshlrev_b32_e32 v110, 16, v13
	v_mov_b32_e32 v116, v107
	v_mov_b32_e32 v117, v105
	v_mov_b32_e32 v120, v109
	v_mov_b32_e32 v121, v111
	v_lshlrev_b32_e32 v89, 16, v9
	v_lshlrev_b32_e32 v88, 16, v8
	v_lshlrev_b32_e32 v93, 16, v11
	v_lshlrev_b32_e32 v92, 16, v10
	v_and_b32_e32 v97, 0xffff0000, v16
	v_and_b32_e32 v99, 0xffff0000, v17
	v_and_b32_e32 v101, 0xffff0000, v18
	v_and_b32_e32 v103, 0xffff0000, v19
	v_pk_mul_f32 v[8:9], v[90:91], v[90:91]
	v_pk_mul_f32 v[10:11], v[94:95], v[94:95]
	v_mov_b32_e32 v114, v106
	v_mov_b32_e32 v115, v104
	v_mov_b32_e32 v118, v108
	v_mov_b32_e32 v119, v110
	v_lshlrev_b32_e32 v53, 16, v44
	v_lshlrev_b32_e32 v52, 16, v43
	v_and_b32_e32 v51, 0xffff0000, v44
	v_and_b32_e32 v50, 0xffff0000, v43
	v_lshlrev_b32_e32 v57, 16, v45
	v_lshlrev_b32_e32 v56, 16, v42
	v_and_b32_e32 v55, 0xffff0000, v45
	v_and_b32_e32 v54, 0xffff0000, v42
	v_lshlrev_b32_e32 v47, 16, v77
	v_lshlrev_b32_e32 v46, 16, v76
	v_and_b32_e32 v45, 0xffff0000, v77
	v_and_b32_e32 v44, 0xffff0000, v76
	v_lshlrev_b32_e32 v49, 16, v79
	v_lshlrev_b32_e32 v48, 16, v78
	v_and_b32_e32 v43, 0xffff0000, v79
	v_and_b32_e32 v42, 0xffff0000, v78
; __device__ __forceinline__ float bflo(unsigned w) { return __uint_as_float(w << 16); }
; __device__ __forceinline__ float bfhi(unsigned w) { return __uint_as_float(w & 0xffff0000u); }
; __device__ __forceinline__ void rms_row_bf16_to_f32(const bf16* hrow, const float* g, float* orow, int lane) {
;     ...
;     for (int j = 0; j < 8; ++j) { v[j] = hr[64 * j];
;         const float a0 = bflo(v[j].x), a1 = bfhi(v[j].x), a2 = bflo(v[j].y), a3 = bfhi(v[j].y), a4 = bflo(v[j].z), a5 = bfhi(v[j].z), a6 = bflo(v[j].w), a7 = bfhi(v[j].w);
;         s += ((a0 * a0 + a1 * a1) + (a2 * a2 + a3 * a3)) + ((a4 * a4 + a5 * a5) + (a6 * a6 + a7 * a7)); }
;     const float inv = 1.0f / sqrtf(wave_sum(s) * (1.f / DM) + EPS);
	v_pk_mul_f32 v[76:77], v[116:117], v[116:117]
	v_pk_mul_f32 v[78:79], v[120:121], v[120:121]
	v_lshlrev_b32_e32 v96, 16, v16
	v_lshlrev_b32_e32 v98, 16, v17
	v_lshlrev_b32_e32 v100, 16, v18
	v_lshlrev_b32_e32 v102, 16, v19
	v_lshlrev_b32_e32 v58, 16, v22
	v_and_b32_e32 v59, 0xffff0000, v22
	v_lshlrev_b32_e32 v60, 16, v23
	v_and_b32_e32 v61, 0xffff0000, v23
	v_lshlrev_b32_e32 v64, 16, v20
	v_and_b32_e32 v65, 0xffff0000, v20
	v_lshlrev_b32_e32 v112, 16, v21
	v_and_b32_e32 v113, 0xffff0000, v21
	v_mul_f32_e32 v12, v97, v97
	v_mul_f32_e32 v14, v99, v99
	v_mul_f32_e32 v16, v101, v101
	v_mul_f32_e32 v18, v103, v103
	v_pk_fma_f32 v[130:131], v[88:89], v[88:89], v[8:9]
	v_pk_fma_f32 v[132:133], v[92:93], v[92:93], v[10:11]
	v_pk_fma_f32 v[76:77], v[114:115], v[114:115], v[76:77]
	v_pk_fma_f32 v[78:79], v[118:119], v[118:119], v[78:79]
	v_pk_mul_f32 v[122:123], v[58:59], v[58:59]
	v_pk_mul_f32 v[124:125], v[60:61], v[60:61]
	v_pk_mul_f32 v[126:127], v[64:65], v[64:65]
	v_pk_mul_f32 v[128:129], v[112:113], v[112:113]
	v_pk_fma_f32 v[134:135], v[96:97], v[96:97], v[12:13] op_sel_hi:[1,1,0]
	v_pk_fma_f32 v[136:137], v[98:99], v[98:99], v[14:15] op_sel_hi:[1,1,0]
	v_pk_fma_f32 v[138:139], v[100:101], v[100:101], v[16:17] op_sel_hi:[1,1,0]
	v_pk_fma_f32 v[140:141], v[102:103], v[102:103], v[18:19] op_sel_hi:[1,1,0]
	v_lshlrev_b32_e32 v18, 16, v80
	v_and_b32_e32 v19, 0xffff0000, v80
	v_lshlrev_b32_e32 v22, 16, v81
	v_and_b32_e32 v23, 0xffff0000, v81
	v_lshlrev_b32_e32 v16, 16, v82
	v_and_b32_e32 v17, 0xffff0000, v82
	v_lshlrev_b32_e32 v20, 16, v83
	v_and_b32_e32 v21, 0xffff0000, v83
	v_pk_add_f32 v[80:81], v[130:131], v[130:131] op_sel:[0,1] op_sel_hi:[1,0]
	v_pk_add_f32 v[82:83], v[132:133], v[132:133] op_sel:[1,0] op_sel_hi:[0,1]
	v_pk_add_f32 v[76:77], v[76:77], v[76:77] op_sel:[0,1] op_sel_hi:[1,0]
	v_pk_add_f32 v[78:79], v[78:79], v[78:79] op_sel:[0,1] op_sel_hi:[1,0]
	v_lshlrev_b32_e32 v8, 16, v86
	v_and_b32_e32 v9, 0xffff0000, v86
	v_lshlrev_b32_e32 v10, 16, v87
	v_and_b32_e32 v11, 0xffff0000, v87
	v_lshlrev_b32_e32 v12, 16, v84
	v_and_b32_e32 v13, 0xffff0000, v84
	v_lshlrev_b32_e32 v14, 16, v85
	v_and_b32_e32 v15, 0xffff0000, v85
	v_pk_mul_f32 v[84:85], v[50:51], v[50:51]
	v_pk_mul_f32 v[86:87], v[54:55], v[54:55]
	v_pk_mul_f32 v[116:117], v[44:45], v[44:45]
	v_pk_mul_f32 v[120:121], v[42:43], v[42:43]
	v_mov_b32_e32 v141, v122
	v_mov_b32_e32 v139, v123
	v_mov_b32_e32 v135, v124
	v_mov_b32_e32 v137, v125
	v_mov_b32_e32 v81, v128
	v_mov_b32_e32 v83, v129
	v_mov_b32_e32 v79, v126
	v_mov_b32_e32 v77, v127
	v_pk_fma_f32 v[84:85], v[52:53], v[52:53], v[84:85]
	v_pk_fma_f32 v[86:87], v[56:57], v[56:57], v[86:87]
	v_pk_fma_f32 v[116:117], v[46:47], v[46:47], v[116:117]
	v_pk_fma_f32 v[120:121], v[48:49], v[48:49], v[120:121]
	v_pk_add_f32 v[138:139], v[140:141], v[138:139]
	v_pk_add_f32 v[134:135], v[134:135], v[136:137]
	v_pk_add_f32 v[80:81], v[80:81], v[82:83]
	v_pk_add_f32 v[76:77], v[78:79], v[76:77]
	v_pk_add_f32 v[84:85], v[86:87], v[84:85]
	v_pk_add_f32 v[86:87], v[116:117], v[116:117] op_sel:[0,1] op_sel_hi:[1,0]
	v_pk_add_f32 v[116:117], v[120:121], v[120:121] op_sel:[1,0] op_sel_hi:[0,1]
	v_pk_add_f32 v[120:121], v[134:135], v[138:139]
	v_pk_add_f32 v[76:77], v[76:77], v[80:81]
	v_mul_f32_e32 v66, v19, v19
	v_mul_f32_e32 v130, v23, v23
	v_mul_f32_e32 v132, v17, v17
	v_mul_f32_e32 v142, v21, v21
	v_pk_add_f32 v[76:77], v[76:77], v[120:121]
	v_pk_mul_f32 v[114:115], v[8:9], v[8:9]
	v_pk_mul_f32 v[118:119], v[10:11], v[10:11]
	v_pk_mul_f32 v[122:123], v[12:13], v[12:13]
	v_pk_mul_f32 v[124:125], v[14:15], v[14:15]
	v_pk_fma_f32 v[144:145], v[18:19], v[18:19], v[66:67] op_sel_hi:[1,1,0]
	v_pk_fma_f32 v[130:131], v[22:23], v[22:23], v[130:131] op_sel_hi:[1,1,0]
	v_pk_fma_f32 v[132:133], v[16:17], v[16:17], v[132:133] op_sel_hi:[1,1,0]
	v_pk_fma_f32 v[142:143], v[20:21], v[20:21], v[142:143] op_sel_hi:[1,1,0]
	v_pk_add_f32 v[82:83], v[84:85], v[84:85] op_sel:[0,1] op_sel_hi:[1,0]
	v_pk_add_f32 v[76:77], v[76:77], v[76:77] op_sel:[0,1] op_sel_hi:[1,0]
	v_mov_b32_e32 v143, v114
	v_mov_b32_e32 v133, v115
	v_mov_b32_e32 v145, v118
	v_mov_b32_e32 v131, v119
	v_mov_b32_e32 v87, v124
	v_mov_b32_e32 v117, v125
	v_mov_b32_e32 v83, v123
	v_mov_b32_e32 v77, v122
	v_pk_add_f32 v[78:79], v[142:143], v[132:133]
	v_pk_add_f32 v[84:85], v[144:145], v[130:131]
	v_pk_add_f32 v[80:81], v[86:87], v[116:117]
	v_pk_add_f32 v[76:77], v[76:77], v[82:83]
	v_pk_add_f32 v[78:79], v[84:85], v[78:79]
	v_pk_add_f32 v[76:77], v[76:77], v[80:81]
	s_nop 0
	v_pk_add_f32 v[76:77], v[76:77], v[78:79]
	s_nop 0
	v_add_f32_e32 v66, v76, v77
	ds_bpermute_b32 v75, v67, v66
	s_waitcnt lgkmcnt(0)
	v_add_f32_e32 v66, v66, v75
	ds_bpermute_b32 v75, v68, v66
	s_waitcnt lgkmcnt(0)
	v_add_f32_e32 v66, v66, v75
	ds_bpermute_b32 v75, v69, v66
	s_waitcnt lgkmcnt(0)
	v_add_f32_e32 v66, v66, v75
	ds_bpermute_b32 v75, v70, v66
	s_waitcnt lgkmcnt(0)
	v_add_f32_e32 v66, v66, v75
	ds_bpermute_b32 v75, v71, v66
	s_waitcnt lgkmcnt(0)
	v_add_f32_e32 v66, v66, v75
	ds_bpermute_b32 v75, v72, v66
	s_waitcnt lgkmcnt(0)
; #define GAS __attribute__((address_space(1)))
; __device__ __forceinline__ float bflo(unsigned w) { return __uint_as_float(w << 16); }
; __device__ __forceinline__ float bfhi(unsigned w) { return __uint_as_float(w & 0xffff0000u); }
; __device__ __forceinline__ void rms_row_bf16_to_f32(const bf16* hrow, const float* g, float* orow, int lane) {
;     ...
;     const float inv = 1.0f / sqrtf(wave_sum(s) * (1.f / DM) + EPS);
; #pragma unroll
;     for (int j = 0; j < 8; ++j) { const int c = 512 * j + 8 * lane; const f32x4 g0 = *(const GAS f32x4*)(g + c), g1 = *(const GAS f32x4*)(g + c + 4);
;         f32x4 o0, o1; o0.x = bflo(v[j].x) * inv * g0.x; o0.y = bfhi(v[j].x) * inv * g0.y; o0.z = bflo(v[j].y) * inv * g0.z; o0.w = bfhi(v[j].y) * inv * g0.w;
;         o1.x = bflo(v[j].z) * inv * g1.x; o1.y = bfhi(v[j].z) * inv * g1.y; o1.z = bflo(v[j].w) * inv * g1.z; o1.w = bfhi(v[j].w) * inv * g1.w;
;         *(GAS f32x4*)(orow + c) = o0; *(GAS f32x4*)(orow + c + 4) = o1; }
	v_add_f32_e32 v66, v66, v75
	v_fmamk_f32 v66, v66, 0x39800000, v73
	v_mul_f32_e32 v75, 0x4f800000, v66
	v_cmp_gt_f32_e32 vcc, s3, v66
	s_nop 1
	v_cndmask_b32_e32 v66, v66, v75, vcc
	v_sqrt_f32_e32 v75, v66
	s_nop 0
	v_add_u32_e32 v76, -1, v75
	v_add_u32_e32 v77, 1, v75
	v_fma_f32 v78, -v76, v75, v66
	v_fma_f32 v79, -v77, v75, v66
	v_cmp_ge_f32_e64 s[0:1], 0, v78
	s_nop 1
	v_cndmask_b32_e64 v75, v75, v76, s[0:1]
	v_cmp_lt_f32_e64 s[0:1], 0, v79
	s_nop 1
	v_cndmask_b32_e64 v75, v75, v77, s[0:1]
	v_mul_f32_e32 v76, 0x37800000, v75
	v_cndmask_b32_e32 v75, v75, v76, vcc
	v_cmp_class_f32_e32 vcc, v66, v74
	s_nop 1
	v_cndmask_b32_e32 v66, v75, v66, vcc
	v_div_scale_f32 v75, s[0:1], v66, v66, 1.0
	v_rcp_f32_e32 v77, v75
	v_div_scale_f32 v76, vcc, 1.0, v66, 1.0
	v_fma_f32 v78, -v75, v77, 1.0
	v_fmac_f32_e32 v77, v78, v77
	v_mul_f32_e32 v78, v76, v77
	v_fma_f32 v79, -v75, v78, v76
	v_fmac_f32_e32 v78, v79, v77
	v_fma_f32 v75, -v75, v78, v76
	v_div_fmas_f32 v75, v75, v77, v78
	v_div_fixup_f32 v66, v75, v66, 1.0
	v_pk_mul_f32 v[76:77], v[66:67], v[108:109] op_sel_hi:[0,1]
	v_pk_mul_f32 v[78:79], v[66:67], v[110:111] op_sel_hi:[0,1]
	v_pk_mul_f32 v[80:81], v[66:67], v[104:105] op_sel_hi:[0,1]
	v_pk_mul_f32 v[82:83], v[66:67], v[106:107] op_sel_hi:[0,1]
	v_pk_mul_f32 v[4:5], v[4:5], v[76:77]
	v_pk_mul_f32 v[6:7], v[6:7], v[78:79]
	v_pk_mul_f32 v[0:1], v[0:1], v[80:81]
	v_pk_mul_f32 v[2:3], v[2:3], v[82:83]
	global_store_dwordx4 v[62:63], v[4:7], off offset:-2064
	global_store_dwordx4 v[62:63], v[0:3], off offset:-2048
	s_nop 1
	v_mov_b64_e32 v[0:1], v[158:159]
	v_mov_b64_e32 v[2:3], v[160:161]
	s_nop 0
	s_nop 1
	v_mov_b64_e32 v[4:5], v[162:163]
	v_mov_b64_e32 v[6:7], v[164:165]
	v_mov_b32_e32 v78, v88
	v_mov_b32_e32 v79, v90
	v_mov_b32_e32 v90, v89
	v_mov_b32_e32 v80, v92
	v_mov_b32_e32 v81, v94
	v_mov_b32_e32 v94, v93
	v_pk_mul_f32 v[78:79], v[66:67], v[78:79] op_sel_hi:[0,1]
	v_pk_mul_f32 v[82:83], v[66:67], v[90:91] op_sel_hi:[0,1]
	v_add_co_u32_e32 v76, vcc, s12, v40
	v_pk_mul_f32 v[80:81], v[66:67], v[80:81] op_sel_hi:[0,1]
	v_pk_mul_f32 v[84:85], v[66:67], v[94:95] op_sel_hi:[0,1]
	v_addc_co_u32_e32 v77, vcc, -1, v41, vcc
	v_pk_mul_f32 v[64:65], v[66:67], v[64:65] op_sel_hi:[0,1]
	v_pk_mul_f32 v[60:61], v[66:67], v[60:61] op_sel_hi:[0,1]
	v_pk_mul_f32 v[58:59], v[66:67], v[58:59] op_sel_hi:[0,1]
	v_pk_mul_f32 v[22:23], v[66:67], v[22:23] op_sel_hi:[0,1]
	v_pk_mul_f32 v[18:19], v[66:67], v[18:19] op_sel_hi:[0,1]
	v_pk_mul_f32 v[20:21], v[66:67], v[20:21] op_sel_hi:[0,1]
	v_pk_mul_f32 v[16:17], v[66:67], v[16:17] op_sel_hi:[0,1]
	v_pk_mul_f32 v[14:15], v[66:67], v[14:15] op_sel_hi:[0,1]
	v_pk_mul_f32 v[12:13], v[66:67], v[12:13] op_sel_hi:[0,1]
	v_pk_mul_f32 v[10:11], v[66:67], v[10:11] op_sel_hi:[0,1]
	v_pk_mul_f32 v[8:9], v[66:67], v[8:9] op_sel_hi:[0,1]
	v_pk_mul_f32 v[0:1], v[0:1], v[78:79]
	v_pk_mul_f32 v[2:3], v[2:3], v[82:83]
	v_pk_mul_f32 v[4:5], v[4:5], v[80:81]
	v_pk_mul_f32 v[6:7], v[6:7], v[84:85]
	global_store_dwordx4 v[62:63], v[0:3], off offset:-16
	global_store_dwordx4 v[76:77], v[4:7], off offset:-4096
	s_nop 1
	v_mov_b64_e32 v[0:1], v[166:167]
	v_mov_b64_e32 v[2:3], v[168:169]
	s_nop 0
	s_nop 1
	v_mov_b64_e32 v[4:5], v[170:171]
	v_mov_b64_e32 v[6:7], v[172:173]
	v_pk_mul_f32 v[62:63], v[66:67], v[98:99] op_sel_hi:[0,1]
	v_pk_mul_f32 v[78:79], v[66:67], v[96:97] op_sel_hi:[0,1]
	v_pk_mul_f32 v[80:81], v[66:67], v[102:103] op_sel_hi:[0,1]
	v_pk_mul_f32 v[82:83], v[66:67], v[100:101] op_sel_hi:[0,1]
	v_pk_mul_f32 v[0:1], v[0:1], v[78:79]
	v_pk_mul_f32 v[2:3], v[2:3], v[62:63]
	v_pk_mul_f32 v[4:5], v[82:83], v[4:5]
	v_pk_mul_f32 v[6:7], v[80:81], v[6:7]
	global_store_dwordx4 v[76:77], v[0:3], off offset:-2064
	global_store_dwordx4 v[76:77], v[4:7], off offset:-2048
	s_nop 1
	v_mov_b64_e32 v[0:1], v[174:175]
	v_mov_b64_e32 v[2:3], v[176:177]
	s_nop 0
	s_nop 1
	v_mov_b64_e32 v[4:5], v[178:179]
	v_mov_b64_e32 v[6:7], v[180:181]
	v_pk_mul_f32 v[62:63], v[66:67], v[112:113] op_sel_hi:[0,1]
	v_pk_mul_f32 v[0:1], v[64:65], v[0:1]
	v_pk_mul_f32 v[2:3], v[62:63], v[2:3]
	v_pk_mul_f32 v[4:5], v[58:59], v[4:5]
	v_pk_mul_f32 v[6:7], v[60:61], v[6:7]
	global_store_dwordx4 v[76:77], v[0:3], off offset:-16
	global_store_dwordx4 v[76:77], v[4:7], off
	s_nop 1
	v_mov_b64_e32 v[0:1], v[182:183]
	v_mov_b64_e32 v[2:3], v[184:185]
	s_nop 0
	s_nop 1
	v_mov_b64_e32 v[4:5], v[186:187]
	v_mov_b64_e32 v[6:7], v[188:189]
	v_mov_b32_e32 v60, v56
	v_mov_b32_e32 v61, v54
	v_mov_b32_e32 v62, v52
	v_mov_b32_e32 v63, v50
	v_add_co_u32_e32 v58, vcc, s13, v40
	v_mov_b32_e32 v50, v53
	v_mov_b32_e32 v54, v57
	v_pk_mul_f32 v[52:53], v[66:67], v[60:61] op_sel_hi:[0,1]
	v_pk_mul_f32 v[56:57], v[66:67], v[62:63] op_sel_hi:[0,1]
	v_addc_co_u32_e32 v59, vcc, -1, v41, vcc
	v_pk_mul_f32 v[50:51], v[66:67], v[50:51] op_sel_hi:[0,1]
	v_pk_mul_f32 v[54:55], v[66:67], v[54:55] op_sel_hi:[0,1]
	v_pk_mul_f32 v[0:1], v[52:53], v[0:1]
	v_pk_mul_f32 v[2:3], v[56:57], v[2:3]
	v_pk_mul_f32 v[4:5], v[50:51], v[4:5]
	v_pk_mul_f32 v[6:7], v[54:55], v[6:7]
	global_store_dwordx4 v[58:59], v[0:3], off offset:-2064
	global_store_dwordx4 v[58:59], v[4:7], off offset:-2048
	s_nop 1
	v_mov_b64_e32 v[0:1], v[190:191]
	v_mov_b64_e32 v[2:3], v[192:193]
	s_nop 0
	s_nop 1
	v_mov_b64_e32 v[4:5], v[194:195]
	v_mov_b64_e32 v[6:7], v[196:197]
	v_mov_b32_e32 v50, v46
	v_mov_b32_e32 v51, v44
	v_mov_b32_e32 v44, v47
	v_mov_b32_e32 v46, v48
	v_mov_b32_e32 v47, v42
	v_mov_b32_e32 v42, v49
	v_pk_mul_f32 v[48:49], v[66:67], v[50:51] op_sel_hi:[0,1]
	v_pk_mul_f32 v[44:45], v[66:67], v[44:45] op_sel_hi:[0,1]
	v_pk_mul_f32 v[46:47], v[66:67], v[46:47] op_sel_hi:[0,1]
	v_pk_mul_f32 v[42:43], v[66:67], v[42:43] op_sel_hi:[0,1]
	v_pk_mul_f32 v[0:1], v[48:49], v[0:1]
	v_pk_mul_f32 v[2:3], v[44:45], v[2:3]
	v_pk_mul_f32 v[4:5], v[46:47], v[4:5]
	v_pk_mul_f32 v[6:7], v[42:43], v[6:7]
	global_store_dwordx4 v[58:59], v[0:3], off offset:-16
	global_store_dwordx4 v[40:41], v[4:7], off offset:-4096
	s_nop 1
	v_mov_b64_e32 v[0:1], v[198:199]
	v_mov_b64_e32 v[2:3], v[200:201]
	s_nop 0
	s_nop 1
	v_mov_b64_e32 v[4:5], v[202:203]
	v_mov_b64_e32 v[6:7], v[204:205]
	v_pk_mul_f32 v[0:1], v[18:19], v[0:1]
	v_pk_mul_f32 v[2:3], v[22:23], v[2:3]
	v_pk_mul_f32 v[4:5], v[16:17], v[4:5]
	v_pk_mul_f32 v[6:7], v[20:21], v[6:7]
	global_store_dwordx4 v[40:41], v[0:3], off offset:-2064
	global_store_dwordx4 v[40:41], v[4:7], off offset:-2048
	s_nop 1
	v_mov_b64_e32 v[0:1], v[206:207]
	v_mov_b64_e32 v[2:3], v[208:209]
	s_nop 0
	s_nop 1
	v_mov_b64_e32 v[4:5], v[210:211]
	v_mov_b64_e32 v[6:7], v[212:213]
	v_pk_mul_f32 v[0:1], v[12:13], v[0:1]
	v_pk_mul_f32 v[2:3], v[14:15], v[2:3]
	v_pk_mul_f32 v[4:5], v[8:9], v[4:5]
	v_pk_mul_f32 v[6:7], v[10:11], v[6:7]
	global_store_dwordx4 v[40:41], v[0:3], off offset:-16
	global_store_dwordx4 v[40:41], v[4:7], off
	v_lshl_add_u64 v[40:41], v[40:41], 0, s[8:9]
	s_cbranch_scc0 .LBB0_1131
